# v8 + attn B and D: row-sum l via f32 VALU adds instead of ones-MFMAs (as done for C)
# speedup vs baseline: 1.0154x; 1.0036x over previous
; #define LAS __attribute__((address_space(3)))
; #define GASA __attribute__((address_space(1)))
; DI unsigned pk2(float lo, float hi) { f32x2 v = {lo, hi}; bf16x2_t b = __builtin_convertvector(v, bf16x2_t); return __builtin_bit_cast(unsigned, b); }
; template <int DQK, int DV, bool BAND>
; DI void attn_unit(const AttnArgs& a, LAS unsigned char* lds, int tid) {
;     ...
;     asm volatile("s_waitcnt lgkmcnt(0)\n\ts_barrier" ::: "memory");
;     __builtin_amdgcn_s_setprio(0);
;     { if (a.lse != nullptr) {
;           if (hi == 0) scr[r32] = m_run;
; #pragma unroll
;           for (int g = 0; g < 4; ++g) { const f32x4 mr = *(const LAS f32x4*)(scr + 8 * g + 4 * hi);
; #pragma unroll
;               for (int e = 0; e < 4; ++e) if (r32 == 0) ((GASA float*)a.lse)[(long)(wid * 32 + 8 * g + 4 * hi + e) * a.lses] = mr[e] + __builtin_amdgcn_logf(lacc[4 * g + e]); } }
;       LAS bf16_t* stg = (LAS bf16_t*)(lds + wid * 8192);
; #pragma unroll
;       for (int g = 0; g < 4; ++g) {
; #pragma unroll
;           for (int e = 0; e < 4; ++e) { const int orow = 8 * g + 4 * hi + e; const float rr = __builtin_amdgcn_rcpf(lacc[4 * g + e]);
; #pragma unroll
;               for (int d = 0; d < NDB; ++d) stg[orow * DV + d * 32 + r32] = (bf16_t)(pk2(o[d][4 * g + e] * rr, 0.f) & 0xffffu); } }
;       constexpr int CPR = DV / 8, RPI = 64 / CPR;
; #pragma unroll
;       for (int i = 0; i < 32 / RPI; ++i) { const int row = i * RPI + lane / CPR, ch = lane % CPR;
;           const u32x4 v = *(const LAS u32x4*)(stg + row * DV + ch * 8); *(GASA u32x4*)((GASA bf16_t*)a.o + (long)(wid * 32 + row) * a.os + ch * 8) = v; }
.LBB0_167:
	s_lshl_b64 s[40:41], s[42:43], 11
	s_add_u32 s24, s72, s40
	s_addc_u32 s42, s73, s41
	s_lshl_b32 s40, s34, 6
	s_ashr_i32 s41, s40, 31
	s_waitcnt lgkmcnt(0)
	s_barrier
	s_lshl_b64 s[40:41], s[40:41], 1
	s_add_u32 s40, s24, s40
	s_addc_u32 s41, s42, s41
	s_setprio 0
	s_nop 1
	v_add_f32_e32 v46, v46, v47
	s_nop 0
	v_mov_b32_e32 v47, v46
	s_nop 1
	v_permlane32_swap_b32_e32 v46, v47
	s_nop 1
	v_add_f32_e32 v46, v46, v47
	ds_write_b32 v171, v46
	s_waitcnt lgkmcnt(0)
	ds_read_b128 v[32:35], v173
	ds_read_b128 v[36:39], v173 offset:32
	ds_read_b128 v[40:43], v173 offset:64
	ds_read_b128 v[44:47], v173 offset:96
	s_waitcnt lgkmcnt(0)
	v_rcp_f32_e32 v32, v32
	s_lshl_b32 s24, s35, 13
	s_add_i32 s24, s24, 0
	v_lshlrev_b32_e32 v48, 1, v157
	v_mul_f32_e32 v0, v0, v32
	v_add3_u32 v48, s24, v48, v186
	v_cvt_pk_bf16_f32 v0, v0, s0
	ds_write_b16 v48, v0
	v_rcp_f32_e32 v0, v33
	v_mul_f32_e32 v16, v16, v32
	v_cvt_pk_bf16_f32 v16, v16, s0
	ds_write_b16 v48, v16 offset:64
	v_mul_f32_e32 v1, v1, v0
	v_cvt_pk_bf16_f32 v1, v1, s0
	ds_write_b16 v48, v1 offset:128
	v_rcp_f32_e32 v1, v34
	v_mul_f32_e32 v0, v17, v0
	v_cvt_pk_bf16_f32 v0, v0, s0
	ds_write_b16 v48, v0 offset:192
	v_mul_f32_e32 v0, v2, v1
	v_cvt_pk_bf16_f32 v0, v0, s0
	ds_write_b16 v48, v0 offset:256
	v_rcp_f32_e32 v0, v35
	v_mul_f32_e32 v1, v18, v1
	v_cvt_pk_bf16_f32 v1, v1, s0
	ds_write_b16 v48, v1 offset:320
	v_mul_f32_e32 v1, v3, v0
	v_cvt_pk_bf16_f32 v1, v1, s0
	ds_write_b16 v48, v1 offset:384
	v_rcp_f32_e32 v1, v36
	v_mul_f32_e32 v0, v19, v0
	v_cvt_pk_bf16_f32 v0, v0, s0
	ds_write_b16 v48, v0 offset:448
	v_mul_f32_e32 v0, v4, v1
	v_cvt_pk_bf16_f32 v0, v0, s0
	ds_write_b16 v48, v0 offset:1024
	v_rcp_f32_e32 v0, v37
	v_mul_f32_e32 v1, v20, v1
	v_cvt_pk_bf16_f32 v1, v1, s0
	ds_write_b16 v48, v1 offset:1088
	v_mul_f32_e32 v1, v5, v0
	v_cvt_pk_bf16_f32 v1, v1, s0
	ds_write_b16 v48, v1 offset:1152
	v_rcp_f32_e32 v1, v38
	v_mul_f32_e32 v0, v21, v0
	v_cvt_pk_bf16_f32 v0, v0, s0
	ds_write_b16 v48, v0 offset:1216
	v_mul_f32_e32 v0, v6, v1
	v_cvt_pk_bf16_f32 v0, v0, s0
	ds_write_b16 v48, v0 offset:1280
	v_rcp_f32_e32 v0, v39
	v_mul_f32_e32 v1, v22, v1
	v_cvt_pk_bf16_f32 v1, v1, s0
	ds_write_b16 v48, v1 offset:1344
	v_mul_f32_e32 v1, v7, v0
	v_cvt_pk_bf16_f32 v1, v1, s0
	ds_write_b16 v48, v1 offset:1408
	v_rcp_f32_e32 v1, v40
	v_mul_f32_e32 v0, v23, v0
	v_cvt_pk_bf16_f32 v0, v0, s0
	ds_write_b16 v48, v0 offset:1472
	v_mul_f32_e32 v0, v8, v1
	v_cvt_pk_bf16_f32 v0, v0, s0
	ds_write_b16 v48, v0 offset:2048
	v_rcp_f32_e32 v0, v41
	v_mul_f32_e32 v1, v24, v1
	v_cvt_pk_bf16_f32 v1, v1, s0
	ds_write_b16 v48, v1 offset:2112
	v_mul_f32_e32 v1, v9, v0
	v_cvt_pk_bf16_f32 v1, v1, s0
	ds_write_b16 v48, v1 offset:2176
	v_rcp_f32_e32 v1, v42
	v_mul_f32_e32 v0, v25, v0
	v_cvt_pk_bf16_f32 v0, v0, s0
	ds_write_b16 v48, v0 offset:2240
	v_mul_f32_e32 v0, v10, v1
	v_cvt_pk_bf16_f32 v0, v0, s0
	ds_write_b16 v48, v0 offset:2304
	v_rcp_f32_e32 v0, v43
	v_mul_f32_e32 v1, v26, v1
	v_cvt_pk_bf16_f32 v1, v1, s0
	ds_write_b16 v48, v1 offset:2368
	v_mul_f32_e32 v1, v11, v0
	v_cvt_pk_bf16_f32 v1, v1, s0
	ds_write_b16 v48, v1 offset:2432
	v_rcp_f32_e32 v1, v44
	v_mul_f32_e32 v0, v27, v0
	v_cvt_pk_bf16_f32 v0, v0, s0
	ds_write_b16 v48, v0 offset:2496
	v_mul_f32_e32 v0, v12, v1
	v_cvt_pk_bf16_f32 v0, v0, s0
	ds_write_b16 v48, v0 offset:3072
	v_rcp_f32_e32 v0, v45
	v_mul_f32_e32 v1, v28, v1
	v_cvt_pk_bf16_f32 v1, v1, s0
	ds_write_b16 v48, v1 offset:3136
	v_mul_f32_e32 v1, v13, v0
	v_cvt_pk_bf16_f32 v1, v1, s0
	ds_write_b16 v48, v1 offset:3200
	v_rcp_f32_e32 v1, v46
	v_mul_f32_e32 v0, v29, v0
	v_cvt_pk_bf16_f32 v0, v0, s0
	ds_write_b16 v48, v0 offset:3264
	v_mul_f32_e32 v0, v14, v1
	v_cvt_pk_bf16_f32 v0, v0, s0
	ds_write_b16 v48, v0 offset:3328
	v_rcp_f32_e32 v0, v47
	v_mul_f32_e32 v1, v30, v1
	v_cvt_pk_bf16_f32 v1, v1, s0
	ds_write_b16 v48, v1 offset:3392
	v_mul_f32_e32 v1, v15, v0
	v_mul_f32_e32 v0, v31, v0
	v_cvt_pk_bf16_f32 v0, v0, s0
	v_add_u32_e32 v10, s24, v172
	v_cvt_pk_bf16_f32 v1, v1, s0
	ds_write_b16 v48, v0 offset:3520
	v_add_u32_e32 v0, v10, v188
	ds_write_b16 v48, v1 offset:3456
	ds_read_b128 v[0:3], v0
	v_or_b32_e32 v4, s27, v187
	v_ashrrev_i32_e32 v5, 31, v4
	v_lshlrev_b64 v[4:5], 11, v[4:5]
	v_lshl_add_u64 v[4:5], s[40:41], 0, v[4:5]
	v_mov_b32_e32 v173, v195
	v_lshl_add_u64 v[8:9], v[4:5], 0, v[172:173]
	v_add_u32_e32 v4, v10, v190
	ds_read_b128 v[4:7], v4
	s_waitcnt lgkmcnt(1)
	global_store_dwordx4 v[8:9], v[0:3], off
	s_add_i32 s26, s26, s58
	v_readlane_b32 s24, v254, 23
	v_or_b32_e32 v0, s27, v189
	v_ashrrev_i32_e32 v1, 31, v0
	v_lshlrev_b64 v[0:1], 11, v[0:1]
	v_lshl_add_u64 v[0:1], s[40:41], 0, v[0:1]
	v_lshl_add_u64 v[0:1], v[0:1], 0, v[172:173]
	s_waitcnt lgkmcnt(0)
	global_store_dwordx4 v[0:1], v[4:7], off
	v_add_u32_e32 v0, v10, v196
	ds_read_b128 v[0:3], v0
	v_or_b32_e32 v4, s27, v191
	v_ashrrev_i32_e32 v5, 31, v4
	v_lshlrev_b64 v[4:5], 11, v[4:5]
	v_lshl_add_u64 v[4:5], s[40:41], 0, v[4:5]
	v_lshl_add_u64 v[8:9], v[4:5], 0, v[172:173]
	v_add_u32_e32 v4, v10, v199
	ds_read_b128 v[4:7], v4
	s_waitcnt lgkmcnt(1)
	global_store_dwordx4 v[8:9], v[0:3], off
	v_readlane_b32 s70, v255, 6
	s_cmp_ge_i32 s26, s24
	v_or_b32_e32 v0, s27, v198
	v_ashrrev_i32_e32 v1, 31, v0
	v_lshlrev_b64 v[0:1], 11, v[0:1]
	v_lshl_add_u64 v[0:1], s[40:41], 0, v[0:1]
	v_lshl_add_u64 v[0:1], v[0:1], 0, v[172:173]
	v_readlane_b32 s71, v255, 7
	s_waitcnt lgkmcnt(0)
	global_store_dwordx4 v[0:1], v[4:7], off
	s_barrier
	s_cbranch_scc1 .LBB0_202

; template <int DQK, int DV, bool BAND>
; DI void attn_unit(const AttnArgs& a, LAS unsigned char* lds, int tid) {
;     ...
;             const LAS unsigned char* kb = lds + KBUF + vcur + hi * 1024 + r32 * 16;
; #pragma unroll
;             for (int dg = 0; dg < ND0; dg += KG) {
;                 bf16x8 kf0[KG], kf1[KG];
; #pragma unroll
;                 for (int j = 0; j < KG; ++j) if (dg + j < ND0) { kf0[j] = *(const LAS bf16x8*)(kb + (dg + j) * 2048); kf1[j] = *(const LAS bf16x8*)(kb + (dg + j) * 2048 + 512); }
;                 __builtin_amdgcn_sched_barrier(0);
; #pragma unroll
;                 for (int j = 0; j < KG; ++j) if (dg + j < ND0) {
;                     if (dg + j == 0) { p0 = MFMA32(kf0[j], qf[0], negm); p1 = MFMA32(kf1[j], qf[0], negm); }
;                     else { p0 = MFMA32(kf0[j], qf[dg + j], p0); p1 = MFMA32(kf1[j], qf[dg + j], p1); }
;                 }
;             }
;             s16x4 vlo[8], vhi[8];
;             if (VPRE) { const LAS unsigned char* vp_ = lds + VBUF + vcur + ((lane >> 4) & 1) * 32 + (lane & 3) * 8 + (4 * hi + ((lane & 15) >> 2)) * 64;
; #pragma unroll
;               for (int d = 0; d < 2; ++d)
; #pragma unroll
;                   for (int ks = 0; ks < 4; ++ks) { vlo[d * 4 + ks] = vtr(vp_ + d * 4096 + ks * 1024); vhi[d * 4 + ks] = vtr(vp_ + d * 4096 + ks * 1024 + 512); } }
;             __builtin_amdgcn_sched_barrier(0);
;             if (BAND) { const int qi = qw + r32; const int kb0 = 64 * t + 4 * hi;
; #pragma unroll
;                 for (int r = 0; r < 16; ++r) { const int kv = kb0 + (r & 3) + 8 * (r >> 2); int d = qi - kv; d = d < 0 ? -d : d; if (d > 64) p0[r] = -1e30f; int d2 = qi - kv - 32; d2 = d2 < 0 ? -d2 : d2; if (d2 > 64) p1[r] = -1e30f; } }
;             if (!a.nomax) {
;             float mx = fmaxf(p0[0], p1[0]);
; #pragma unroll
;             for (int r = 1; r < 16; ++r) mx = fmaxf(fmaxf(mx, p0[r]), p1[r]);
;             { const unsigned mu = __float_as_uint(mx); auto rr = __builtin_amdgcn_permlane32_swap(mu, mu, false, false); mx = fmaxf(__uint_as_float(rr[0]), __uint_as_float(rr[1])); }
;             if (first || __any(mx > 8.0f)) {
;                 const float delta = first ? fmaxf(mx, -1e4f) : fmaxf(mx, 0.f);
;                 m_run += delta;
; #pragma unroll
;                 for (int r = 0; r < 16; ++r) { p0[r] -= delta; p1[r] -= delta; negm[r] = -m_run; }
;                 if (!first) {
.Ld_skip_t2:
	v_lshl_add_u64 v[0:1], v[0:1], 0, v[194:195]
	s_mov_b64 s[46:47], 0x80080
	v_lshl_add_u64 v[0:1], v[0:1], 0, s[46:47]
	s_add_i32 s92, s92, 0x14000
	s_mov_b32 s24, m0
	s_mov_b32 m0, s92
	s_nop 0
	global_load_lds_dwordx4 v[0:1], off
	s_mov_b32 m0, s24
	ds_read_b128 v[0:3], v183
	ds_read_b128 v[20:23], v183 offset:512
	ds_read_b128 v[24:27], v183 offset:2048
	ds_read_b128 v[28:31], v183 offset:2560
	ds_read_b128 v[32:35], v183 offset:4096
	ds_read_b128 v[36:39], v183 offset:4608
	ds_read_b128 v[40:43], v183 offset:6144
	ds_read_b128 v[44:47], v183 offset:6656
	s_movk_i32 s49, 0x4000
	s_mov_b32 s46, 1
	v_lshl_add_u32 v171, v157, 2, s81
	v_lshl_add_u32 v173, v184, 2, s81
	s_waitcnt lgkmcnt(7)
	v_mfma_f32_32x32x16_bf16 v[4:19], v[0:3], v[96:99], 0
	s_waitcnt lgkmcnt(6)
	v_mfma_f32_32x32x16_bf16 v[48:63], v[20:23], v[96:99], 0
	s_waitcnt lgkmcnt(5)
	v_mfma_f32_32x32x16_bf16 v[4:19], v[24:27], v[100:103], v[4:19]
	s_waitcnt lgkmcnt(4)
	v_mfma_f32_32x32x16_bf16 v[48:63], v[28:31], v[100:103], v[48:63]
	ds_read_b128 v[0:3], v183 offset:8192
	ds_read_b128 v[20:23], v183 offset:8704
	ds_read_b128 v[24:27], v183 offset:10240
	ds_read_b128 v[28:31], v183 offset:10752
	s_waitcnt lgkmcnt(7)
	v_mfma_f32_32x32x16_bf16 v[4:19], v[32:35], v[104:107], v[4:19]
	s_waitcnt lgkmcnt(6)
	v_mfma_f32_32x32x16_bf16 v[48:63], v[36:39], v[104:107], v[48:63]
	s_waitcnt lgkmcnt(5)
	v_mfma_f32_32x32x16_bf16 v[4:19], v[40:43], v[108:111], v[4:19]
	s_waitcnt lgkmcnt(4)
	v_mfma_f32_32x32x16_bf16 v[48:63], v[44:47], v[108:111], v[48:63]
	s_waitcnt lgkmcnt(3)
	v_mfma_f32_32x32x16_bf16 v[4:19], v[0:3], v[112:115], v[4:19]
	s_waitcnt lgkmcnt(2)
	v_mfma_f32_32x32x16_bf16 v[48:63], v[20:23], v[112:115], v[48:63]
	ds_read_b64_tr_b16 v[0:1], v185 offset:49152
	ds_read_b64_tr_b16 v[2:3], v185 offset:49664
	ds_read_b64_tr_b16 v[64:65], v185 offset:50176
	ds_read_b64_tr_b16 v[66:67], v185 offset:50688
	ds_read_b64_tr_b16 v[68:69], v185 offset:51200
	ds_read_b64_tr_b16 v[70:71], v185 offset:51712
	ds_read_b64_tr_b16 v[72:73], v185 offset:52224
	ds_read_b64_tr_b16 v[74:75], v185 offset:52736
	ds_read_b64_tr_b16 v[20:21], v185 offset:53248
	ds_read_b64_tr_b16 v[22:23], v185 offset:53760
	ds_read_b64_tr_b16 v[76:77], v185 offset:54272
	ds_read_b64_tr_b16 v[78:79], v185 offset:54784
	ds_read_b64_tr_b16 v[80:81], v185 offset:55296
	ds_read_b64_tr_b16 v[82:83], v185 offset:55808
	ds_read_b64_tr_b16 v[84:85], v185 offset:56320
	ds_read_b64_tr_b16 v[86:87], v185 offset:56832
	s_waitcnt lgkmcnt(14)
	v_mfma_f32_32x32x16_bf16 v[4:19], v[24:27], v[116:119], v[4:19]
	v_mfma_f32_32x32x16_bf16 v[48:63], v[28:31], v[116:119], v[48:63]
	s_nop 11
	v_max_f32_e32 v24, v48, v48
	v_max_f32_e32 v25, v4, v4
	v_max_f32_e32 v24, v25, v24
	v_max3_f32 v24, v24, v5, v49
	v_max3_f32 v24, v24, v6, v50
	v_max3_f32 v24, v24, v7, v51
	v_max3_f32 v24, v24, v8, v52
	v_max3_f32 v24, v24, v9, v53
	v_max3_f32 v24, v24, v10, v54
	v_max3_f32 v24, v24, v11, v55
	v_max3_f32 v24, v24, v12, v56
	v_max3_f32 v24, v24, v13, v57
	v_max3_f32 v24, v24, v14, v58
	v_max3_f32 v24, v24, v15, v59
	v_max3_f32 v24, v24, v16, v60
	v_max3_f32 v24, v24, v17, v61
	v_max3_f32 v24, v24, v18, v62
	v_max3_f32 v24, v24, v19, v63
	v_mov_b32_e32 v25, v24
	s_nop 1
	v_permlane32_swap_b32_e32 v24, v25
	s_mov_b32 s24, 0xc61c4000
	v_max3_f32 v120, v24, v25, s24
	v_sub_f32_e32 v4, v4, v120
	v_sub_f32_e32 v5, v5, v120
	v_sub_f32_e32 v6, v6, v120
	v_sub_f32_e32 v7, v7, v120
	v_sub_f32_e32 v8, v8, v120
	v_sub_f32_e32 v9, v9, v120
	v_sub_f32_e32 v10, v10, v120
	v_sub_f32_e32 v11, v11, v120
	v_exp_f32_e32 v4, v4
	v_exp_f32_e32 v5, v5
	v_exp_f32_e32 v6, v6
	v_exp_f32_e32 v7, v7
	v_exp_f32_e32 v8, v8
	v_exp_f32_e32 v9, v9
	v_exp_f32_e32 v10, v10
	v_exp_f32_e32 v11, v11
	v_cvt_pk_bf16_f32 v32, v4, v5
	v_cvt_pk_bf16_f32 v33, v6, v7
	v_cvt_pk_bf16_f32 v34, v8, v9
	v_cvt_pk_bf16_f32 v35, v10, v11
	v_add_f32_e32 v46, v4, v5
	v_add_f32_e32 v47, v6, v7
	v_add_f32_e32 v46, v46, v8
	v_add_f32_e32 v47, v47, v9
	v_add_f32_e32 v46, v46, v10
	v_add_f32_e32 v47, v47, v11
	v_sub_f32_e32 v24, v12, v120
	v_sub_f32_e32 v25, v13, v120
	v_exp_f32_e32 v41, v24
	v_exp_f32_e32 v42, v25
	v_sub_f32_e32 v26, v14, v120
	v_sub_f32_e32 v36, v15, v120
	v_sub_f32_e32 v37, v16, v120
	v_sub_f32_e32 v38, v17, v120
	v_sub_f32_e32 v39, v18, v120
	v_sub_f32_e32 v40, v19, v120
	v_exp_f32_e32 v89, v26
	v_exp_f32_e32 v90, v36
	v_exp_f32_e32 v91, v37
	v_exp_f32_e32 v121, v38
	v_exp_f32_e32 v122, v39
	v_exp_f32_e32 v123, v40
	v_mfma_f32_32x32x16_bf16 v[0:15], v[32:35], v[0:3], 0
	v_add_f32_e32 v46, v46, v41
	v_add_f32_e32 v47, v47, v42
	v_add_f32_e32 v46, v46, v89
	v_add_f32_e32 v47, v47, v90
	v_add_f32_e32 v46, v46, v91
	v_add_f32_e32 v47, v47, v121
	v_add_f32_e32 v46, v46, v122
	v_add_f32_e32 v47, v47, v123
	v_cvt_pk_bf16_f32 v88, v41, v42
	v_cvt_pk_bf16_f32 v89, v89, v90
	v_cvt_pk_bf16_f32 v90, v91, v121
	v_cvt_pk_bf16_f32 v91, v122, v123
	v_sub_f32_e32 v48, v48, v120
	v_sub_f32_e32 v49, v49, v120
	v_sub_f32_e32 v50, v50, v120
	s_waitcnt lgkmcnt(6)
; #define LAS __attribute__((address_space(3)))
; DI unsigned pk2(float lo, float hi) { f32x2 v = {lo, hi}; bf16x2_t b = __builtin_convertvector(v, bf16x2_t); return __builtin_bit_cast(unsigned, b); }
; #define MFMA32(a, b, c) __builtin_amdgcn_mfma_f32_32x32x16_bf16((a), (b), (c), 0, 0, 0)
; DI s16x4 vtr(const LAS unsigned char* p) { return __builtin_bit_cast(s16x4, __builtin_amdgcn_ds_read_tr16_b64_v4i16((LAS v4i16_t*)p)); }
; template <int DQK, int DV, bool BAND>
; DI void attn_unit(const AttnArgs& a, LAS unsigned char* lds, int tid) {
;     ...
;             for (int r = 0; r < 16; ++r) { p0[r] = __builtin_amdgcn_exp2f(p0[r]); p1[r] = __builtin_amdgcn_exp2f(p1[r]); }
;             { u32x4 w;
;               w.x = pk2(p0[0], p0[1]); w.y = pk2(p0[2], p0[3]); w.z = pk2(p0[4], p0[5]); w.w = pk2(p0[6], p0[7]); pa[0] = __builtin_bit_cast(bf16x8, w);
;               w.x = pk2(p0[8], p0[9]); w.y = pk2(p0[10], p0[11]); w.z = pk2(p0[12], p0[13]); w.w = pk2(p0[14], p0[15]); pa[1] = __builtin_bit_cast(bf16x8, w);
;               w.x = pk2(p1[0], p1[1]); w.y = pk2(p1[2], p1[3]); w.z = pk2(p1[4], p1[5]); w.w = pk2(p1[6], p1[7]); pa[2] = __builtin_bit_cast(bf16x8, w);
;               w.x = pk2(p1[8], p1[9]); w.y = pk2(p1[10], p1[11]); w.z = pk2(p1[12], p1[13]); w.w = pk2(p1[14], p1[15]); pa[3] = __builtin_bit_cast(bf16x8, w); }
;             if (DQK > 96) { AT_PV(vcur); } else {
;                 if (!VPRE) { const LAS unsigned char* vp_ = lds + VBUF + vcur + ((lane >> 4) & 1) * 32 + (lane & 3) * 8 + (4 * hi + ((lane & 15) >> 2)) * 64;
; #pragma unroll
;                     for (int d = 0; d < 2; ++d)
; #pragma unroll
;                         for (int ks = 0; ks < 4; ++ks) { vlo[d * 4 + ks] = vtr(vp_ + d * 4096 + ks * 1024); vhi[d * 4 + ks] = vtr(vp_ + d * 4096 + ks * 1024 + 512); }
;                     __builtin_amdgcn_sched_barrier(0); }
; #pragma unroll
;                 for (int ks = 0; ks < 4; ++ks) {
; #pragma unroll
;                     for (int d = 0; d < 2; ++d) { const s16x4 lo = vlo[d * 4 + ks], hh = vhi[d * 4 + ks];
;                         const bf16x8 vf = (bf16x8){lo[0], lo[1], lo[2], lo[3], hh[0], hh[1], hh[2], hh[3]}; o[d] = MFMA32(pa[ks], vf, o[d]); }
;                     lacc = MFMA32(pa[ks], ones, lacc); }
	v_mfma_f32_32x32x16_bf16 v[16:31], v[32:35], v[20:23], 0
	v_sub_f32_e32 v51, v51, v120
	v_sub_f32_e32 v52, v52, v120
	v_sub_f32_e32 v53, v53, v120
	v_sub_f32_e32 v54, v54, v120
	v_sub_f32_e32 v55, v55, v120
	v_exp_f32_e32 v48, v48
	v_exp_f32_e32 v49, v49
	v_exp_f32_e32 v50, v50
	v_exp_f32_e32 v51, v51
	v_exp_f32_e32 v52, v52
	v_exp_f32_e32 v53, v53
	v_exp_f32_e32 v54, v54
	v_exp_f32_e32 v55, v55
	v_add_f32_e32 v46, v46, v48
	v_add_f32_e32 v47, v47, v49
	v_add_f32_e32 v46, v46, v50
	v_add_f32_e32 v47, v47, v51
	v_add_f32_e32 v46, v46, v52
	v_add_f32_e32 v47, v47, v53
	v_add_f32_e32 v46, v46, v54
	v_add_f32_e32 v47, v47, v55
	v_cvt_pk_bf16_f32 v48, v48, v49
	v_mfma_f32_32x32x16_bf16 v[0:15], v[88:91], v[64:67], v[0:15]
	v_cvt_pk_bf16_f32 v49, v50, v51
	v_cvt_pk_bf16_f32 v50, v52, v53
	v_cvt_pk_bf16_f32 v51, v54, v55
	v_sub_f32_e32 v52, v56, v120
	v_sub_f32_e32 v53, v57, v120
	v_sub_f32_e32 v54, v58, v120
	v_sub_f32_e32 v55, v59, v120
	s_waitcnt lgkmcnt(4)
	v_mfma_f32_32x32x16_bf16 v[16:31], v[88:91], v[76:79], v[16:31]
	v_sub_f32_e32 v56, v60, v120
	v_sub_f32_e32 v57, v61, v120
	v_sub_f32_e32 v58, v62, v120
	v_sub_f32_e32 v59, v63, v120
	v_exp_f32_e32 v52, v52
	v_exp_f32_e32 v53, v53
	v_exp_f32_e32 v54, v54
	v_exp_f32_e32 v55, v55
	v_exp_f32_e32 v56, v56
	v_exp_f32_e32 v57, v57
	v_exp_f32_e32 v58, v58
	v_exp_f32_e32 v59, v59
	v_add_f32_e32 v46, v46, v52
	v_add_f32_e32 v47, v47, v53
	v_add_f32_e32 v46, v46, v54
	v_add_f32_e32 v47, v47, v55
	v_add_f32_e32 v46, v46, v56
	v_add_f32_e32 v47, v47, v57
	v_add_f32_e32 v46, v46, v58
	v_add_f32_e32 v47, v47, v59
	v_cvt_pk_bf16_f32 v52, v52, v53
	v_cvt_pk_bf16_f32 v53, v54, v55
	v_mfma_f32_32x32x16_bf16 v[0:15], v[48:51], v[68:71], v[0:15]
	v_cvt_pk_bf16_f32 v54, v56, v57
	v_cvt_pk_bf16_f32 v55, v58, v59
	s_add_u32 s24, s70, s66
	s_addc_u32 s47, s71, s67
	s_add_u32 s56, s24, s56
	s_addc_u32 s57, s47, s57
	s_add_u32 s40, s64, s40
	s_waitcnt lgkmcnt(2)
	v_mfma_f32_32x32x16_bf16 v[16:31], v[48:51], v[80:83], v[16:31]
	s_addc_u32 s41, s65, s41
	v_add_f32_e32 v200, 0, v120
	v_add_lshl_u32 v194, v182, s95, 12
	v_lshl_add_u64 v[178:179], v[168:169], 0, s[40:41]
	s_add_u32 s40, s64, s72
	s_addc_u32 s41, s65, s73
	v_readlane_b32 s72, v255, 4
	v_xor_b32_e32 v48, 0x80000000, v200
	v_lshl_add_u64 v[50:51], s[56:57], 0, v[194:195]
	v_lshl_add_u64 v[174:175], v[166:167], 0, v[50:51]
	v_lshl_add_u64 v[180:181], v[168:169], 0, s[40:41]
	s_mov_b32 s47, 3
	v_mov_b32_e32 v49, v48
	v_mov_b32_e32 v50, v48
	v_mfma_f32_32x32x16_bf16 v[0:15], v[52:55], v[72:75], v[0:15]
	v_mov_b32_e32 v51, v48
	v_mov_b32_e32 v56, v48
	v_mov_b32_e32 v57, v48
	v_mov_b32_e32 v58, v48
	v_mov_b32_e32 v59, v48
	v_mov_b32_e32 v60, v48
	v_mov_b32_e32 v61, v48
	s_waitcnt lgkmcnt(0)
	v_mfma_f32_32x32x16_bf16 v[16:31], v[52:55], v[84:87], v[16:31]
	v_mov_b32_e32 v62, v48
	v_mov_b32_e32 v63, v48
	v_readlane_b32 s64, v253, 57
	v_readlane_b32 s67, v253, 59
	v_readlane_b32 s66, v253, 60
	s_movk_i32 s95, 0xc00
	s_mov_b32 s90, 0x41000000
	v_mov_b32_e32 v52, v48
	v_mov_b32_e32 v53, v48
	v_mov_b32_e32 v54, v48
	v_mov_b32_e32 v55, v48
	s_mov_b64 s[70:71], 0x1000
	s_mov_b64 s[74:75], 0x60000
	s_mov_b64 s[76:77], 0x30000
	v_readlane_b32 s91, v254, 40
	v_readlane_b32 s73, v255, 5
	v_readlane_b32 s65, v253, 58
	s_add_i32 s24, s47, -1
	s_cmp_ge_u32 s24, s69
	s_mov_b64 s[40:41], -1
	s_cbranch_scc0 .LBB0_188

; template <int DQK, int DV, bool BAND>
; DI void attn_unit(const AttnArgs& a, LAS unsigned char* lds, int tid) {
;     ...
;             const LAS unsigned char* kb = lds + KBUF + vcur + hi * 1024 + r32 * 16;
; #pragma unroll
;             for (int dg = 0; dg < ND0; dg += KG) {
;                 bf16x8 kf0[KG], kf1[KG];
; #pragma unroll
;                 for (int j = 0; j < KG; ++j) if (dg + j < ND0) { kf0[j] = *(const LAS bf16x8*)(kb + (dg + j) * 2048); kf1[j] = *(const LAS bf16x8*)(kb + (dg + j) * 2048 + 512); }
;                 __builtin_amdgcn_sched_barrier(0);
; #pragma unroll
;                 for (int j = 0; j < KG; ++j) if (dg + j < ND0) {
;                     if (dg + j == 0) { p0 = MFMA32(kf0[j], qf[0], negm); p1 = MFMA32(kf1[j], qf[0], negm); }
;                     else { p0 = MFMA32(kf0[j], qf[dg + j], p0); p1 = MFMA32(kf1[j], qf[dg + j], p1); }
;                 }
;             }
;             s16x4 vlo[8], vhi[8];
;             if (VPRE) { const LAS unsigned char* vp_ = lds + VBUF + vcur + ((lane >> 4) & 1) * 32 + (lane & 3) * 8 + (4 * hi + ((lane & 15) >> 2)) * 64;
; #pragma unroll
;               for (int d = 0; d < 2; ++d)
; #pragma unroll
;                   for (int ks = 0; ks < 4; ++ks) { vlo[d * 4 + ks] = vtr(vp_ + d * 4096 + ks * 1024); vhi[d * 4 + ks] = vtr(vp_ + d * 4096 + ks * 1024 + 512); } }
;             __builtin_amdgcn_sched_barrier(0);
;             if (BAND) { const int qi = qw + r32; const int kb0 = 64 * t + 4 * hi;
; #pragma unroll
;                 for (int r = 0; r < 16; ++r) { const int kv = kb0 + (r & 3) + 8 * (r >> 2); int d = qi - kv; d = d < 0 ? -d : d; if (d > 64) p0[r] = -1e30f; int d2 = qi - kv - 32; d2 = d2 < 0 ? -d2 : d2; if (d2 > 64) p1[r] = -1e30f; } }
;             if (!a.nomax) {
;             float mx = fmaxf(p0[0], p1[0]);
; #pragma unroll
;             for (int r = 1; r < 16; ++r) mx = fmaxf(fmaxf(mx, p0[r]), p1[r]);
;             { const unsigned mu = __float_as_uint(mx); auto rr = __builtin_amdgcn_permlane32_swap(mu, mu, false, false); mx = fmaxf(__uint_as_float(rr[0]), __uint_as_float(rr[1])); }
;             if (first || __any(mx > 8.0f)) {
;                 const float delta = first ? fmaxf(mx, -1e4f) : fmaxf(mx, 0.f);
;                 m_run += delta;
; #pragma unroll
;                 for (int r = 0; r < 16; ++r) { p0[r] -= delta; p1[r] -= delta; negm[r] = -m_run; }
;                 if (!first) {
.LBB0_196:
	v_add_u32_e32 v148, s49, v183
	ds_read_b128 v[80:83], v148
	ds_read_b128 v[120:123], v148 offset:512
	ds_read_b128 v[124:127], v148 offset:2048
	ds_read_b128 v[128:131], v148 offset:2560
	ds_read_b128 v[132:135], v148 offset:4096
	ds_read_b128 v[136:139], v148 offset:4608
	ds_read_b128 v[140:143], v148 offset:6144
	ds_read_b128 v[144:147], v148 offset:6656
	s_waitcnt lgkmcnt(7)
	v_mfma_f32_32x32x16_bf16 v[64:79], v[80:83], v[96:99], v[48:63]
	v_mov_b64_e32 v[94:95], v[62:63]
	v_mov_b64_e32 v[92:93], v[60:61]
	v_mov_b64_e32 v[90:91], v[58:59]
	v_mov_b64_e32 v[88:89], v[56:57]
	v_mov_b64_e32 v[86:87], v[54:55]
	v_mov_b64_e32 v[84:85], v[52:53]
	v_mov_b64_e32 v[82:83], v[50:51]
	v_mov_b64_e32 v[80:81], v[48:49]
	s_waitcnt lgkmcnt(5)
	v_mfma_f32_32x32x16_bf16 v[64:79], v[124:127], v[100:103], v[64:79]
	v_mfma_f32_32x32x16_bf16 v[80:95], v[120:123], v[96:99], v[80:95]
	s_waitcnt lgkmcnt(4)
	v_mfma_f32_32x32x16_bf16 v[80:95], v[128:131], v[100:103], v[80:95]
	s_waitcnt lgkmcnt(3)
	v_mfma_f32_32x32x16_bf16 v[64:79], v[132:135], v[104:107], v[64:79]
	ds_read_b128 v[120:123], v148 offset:8192
	ds_read_b128 v[124:127], v148 offset:8704
	ds_read_b128 v[128:131], v148 offset:10240
	ds_read_b128 v[132:135], v148 offset:10752
	s_waitcnt lgkmcnt(6)
	v_mfma_f32_32x32x16_bf16 v[80:95], v[136:139], v[104:107], v[80:95]
	s_waitcnt lgkmcnt(5)
	v_mfma_f32_32x32x16_bf16 v[64:79], v[140:143], v[108:111], v[64:79]
	s_waitcnt lgkmcnt(4)
	v_mfma_f32_32x32x16_bf16 v[80:95], v[144:147], v[108:111], v[80:95]
	s_waitcnt lgkmcnt(3)
	v_mfma_f32_32x32x16_bf16 v[64:79], v[120:123], v[112:115], v[64:79]
	s_waitcnt lgkmcnt(2)
	v_mfma_f32_32x32x16_bf16 v[80:95], v[124:127], v[112:115], v[80:95]
	v_add_u32_e32 v126, s49, v185
	s_waitcnt lgkmcnt(1)
	v_mfma_f32_32x32x16_bf16 v[64:79], v[128:131], v[116:119], v[64:79]
	s_waitcnt lgkmcnt(0)
	v_mfma_f32_32x32x16_bf16 v[80:95], v[132:135], v[116:119], v[80:95]
	ds_read_b64_tr_b16 v[148:149], v126 offset:49152
	ds_read_b64_tr_b16 v[150:151], v126 offset:49664
	ds_read_b64_tr_b16 v[140:141], v126 offset:50176
	ds_read_b64_tr_b16 v[142:143], v126 offset:50688
	ds_read_b64_tr_b16 v[132:133], v126 offset:51200
	ds_read_b64_tr_b16 v[134:135], v126 offset:51712
	ds_read_b64_tr_b16 v[120:121], v126 offset:52224
	ds_read_b64_tr_b16 v[122:123], v126 offset:52736
	ds_read_b64_tr_b16 v[144:145], v126 offset:53248
	ds_read_b64_tr_b16 v[146:147], v126 offset:53760
	ds_read_b64_tr_b16 v[136:137], v126 offset:54272
	ds_read_b64_tr_b16 v[138:139], v126 offset:54784
	ds_read_b64_tr_b16 v[128:129], v126 offset:55296
	ds_read_b64_tr_b16 v[130:131], v126 offset:55808
	ds_read_b64_tr_b16 v[124:125], v126 offset:56320
	ds_read_b64_tr_b16 v[126:127], v126 offset:56832
	v_max_f32_e32 v194, v80, v80
	v_max_f32_e32 v201, v64, v64
	v_max_f32_e32 v194, v201, v194
	v_max3_f32 v194, v194, v65, v81
	v_max3_f32 v194, v194, v66, v82
	v_max3_f32 v194, v194, v67, v83
	v_max3_f32 v194, v194, v68, v84
	v_max3_f32 v194, v194, v69, v85
	v_max3_f32 v194, v194, v70, v86
	v_max3_f32 v194, v194, v71, v87
	v_max3_f32 v194, v194, v72, v88
	v_max3_f32 v194, v194, v73, v89
	v_max3_f32 v194, v194, v74, v90
	v_max3_f32 v194, v194, v75, v91
	v_max3_f32 v194, v194, v76, v92
	v_max3_f32 v194, v194, v77, v93
	v_max3_f32 v194, v194, v78, v94
	v_max3_f32 v194, v194, v79, v95
	v_mov_b32_e32 v201, v194
	s_nop 1
	v_permlane32_swap_b32_e32 v194, v201
	v_max_f32_e32 v201, v201, v201
	v_max_f32_e32 v194, v194, v194
	v_max_f32_e32 v194, v194, v201
	v_cmp_lt_f32_e32 vcc, s90, v194
	s_cbranch_vccz .LBB0_200
	v_max_f32_e32 v48, v194, v194
	v_max_f32_e32 v48, 0, v48
	v_exp_f32_e64 v49, -v48
	s_and_saveexec_b64 s[40:41], s[0:1]
	ds_write_b32 v171, v49
	s_or_b64 exec, exec, s[40:41]
	v_mul_f32_e32 v46, v46, v49
	v_mul_f32_e32 v47, v47, v49
	v_add_f32_e32 v200, v200, v48
	v_sub_f32_e32 v64, v64, v48
	v_sub_f32_e32 v65, v65, v48
	v_sub_f32_e32 v66, v66, v48
	v_sub_f32_e32 v67, v67, v48
	v_sub_f32_e32 v68, v68, v48
	v_sub_f32_e32 v69, v69, v48
	v_sub_f32_e32 v70, v70, v48
	v_sub_f32_e32 v71, v71, v48
	v_sub_f32_e32 v72, v72, v48
	v_sub_f32_e32 v73, v73, v48
	v_sub_f32_e32 v74, v74, v48
	v_sub_f32_e32 v75, v75, v48
	v_sub_f32_e32 v76, v76, v48
	v_sub_f32_e32 v77, v77, v48
	v_sub_f32_e32 v78, v78, v48
	v_sub_f32_e32 v79, v79, v48
	v_sub_f32_e32 v80, v80, v48
	v_sub_f32_e32 v81, v81, v48
	v_sub_f32_e32 v82, v82, v48
	v_sub_f32_e32 v83, v83, v48
	v_sub_f32_e32 v84, v84, v48
	v_sub_f32_e32 v85, v85, v48
	v_sub_f32_e32 v86, v86, v48
	v_sub_f32_e32 v87, v87, v48
	v_sub_f32_e32 v88, v88, v48
	v_sub_f32_e32 v89, v89, v48
	v_sub_f32_e32 v90, v90, v48
	v_sub_f32_e32 v91, v91, v48
	v_sub_f32_e32 v92, v92, v48
	v_sub_f32_e32 v93, v93, v48
	v_sub_f32_e32 v94, v94, v48
	v_sub_f32_e32 v95, v95, v48
	ds_read_b128 v[48:51], v173
	ds_read_b128 v[52:55], v173 offset:32
	ds_read_b128 v[56:59], v173 offset:64
	ds_read_b128 v[204:207], v173 offset:96
	v_xor_b32_e32 v63, 0x80000000, v200
	s_waitcnt lgkmcnt(3)
	v_pk_mul_f32 v[18:19], v[18:19], v[50:51]
	s_waitcnt lgkmcnt(2)
	v_pk_mul_f32 v[22:23], v[22:23], v[54:55]
	s_waitcnt lgkmcnt(1)
	v_pk_mul_f32 v[26:27], v[26:27], v[58:59]
	s_waitcnt lgkmcnt(0)
	v_pk_mul_f32 v[30:31], v[30:31], v[206:207]
	v_pk_mul_f32 v[14:15], v[14:15], v[206:207]
	v_pk_mul_f32 v[10:11], v[10:11], v[58:59]
	v_pk_mul_f32 v[6:7], v[6:7], v[54:55]
	v_pk_mul_f32 v[2:3], v[2:3], v[50:51]
	v_pk_mul_f32 v[28:29], v[28:29], v[204:205]
	v_pk_mul_f32 v[24:25], v[24:25], v[56:57]
	v_pk_mul_f32 v[20:21], v[20:21], v[52:53]
	v_pk_mul_f32 v[16:17], v[16:17], v[48:49]
	v_pk_mul_f32 v[12:13], v[12:13], v[204:205]
	v_pk_mul_f32 v[8:9], v[8:9], v[56:57]
	v_pk_mul_f32 v[4:5], v[4:5], v[52:53]
	v_pk_mul_f32 v[0:1], v[0:1], v[48:49]
	v_mov_b32_e32 v62, v63
	v_mov_b32_e32 v61, v63
	v_mov_b32_e32 v60, v63
	v_mov_b32_e32 v59, v63
	v_mov_b32_e32 v58, v63
	v_mov_b32_e32 v57, v63
	v_mov_b32_e32 v56, v63
	v_mov_b32_e32 v55, v63
	v_mov_b32_e32 v54, v63
	v_mov_b32_e32 v53, v63
	v_mov_b32_e32 v52, v63
	v_mov_b32_e32 v51, v63
	v_mov_b32_e32 v50, v63
	v_mov_b32_e32 v49, v63
	v_mov_b32_e32 v48, v63
; #define LAS __attribute__((address_space(3)))
; DI unsigned pk2(float lo, float hi) { f32x2 v = {lo, hi}; bf16x2_t b = __builtin_convertvector(v, bf16x2_t); return __builtin_bit_cast(unsigned, b); }
; #define MFMA32(a, b, c) __builtin_amdgcn_mfma_f32_32x32x16_bf16((a), (b), (c), 0, 0, 0)
; DI s16x4 vtr(const LAS unsigned char* p) { return __builtin_bit_cast(s16x4, __builtin_amdgcn_ds_read_tr16_b64_v4i16((LAS v4i16_t*)p)); }
; template <int DQK, int DV, bool BAND>
; DI void attn_unit(const AttnArgs& a, LAS unsigned char* lds, int tid) {
;     ...
;             for (int r = 0; r < 16; ++r) { p0[r] = __builtin_amdgcn_exp2f(p0[r]); p1[r] = __builtin_amdgcn_exp2f(p1[r]); }
;             { u32x4 w;
;               w.x = pk2(p0[0], p0[1]); w.y = pk2(p0[2], p0[3]); w.z = pk2(p0[4], p0[5]); w.w = pk2(p0[6], p0[7]); pa[0] = __builtin_bit_cast(bf16x8, w);
;               w.x = pk2(p0[8], p0[9]); w.y = pk2(p0[10], p0[11]); w.z = pk2(p0[12], p0[13]); w.w = pk2(p0[14], p0[15]); pa[1] = __builtin_bit_cast(bf16x8, w);
;               w.x = pk2(p1[0], p1[1]); w.y = pk2(p1[2], p1[3]); w.z = pk2(p1[4], p1[5]); w.w = pk2(p1[6], p1[7]); pa[2] = __builtin_bit_cast(bf16x8, w);
;               w.x = pk2(p1[8], p1[9]); w.y = pk2(p1[10], p1[11]); w.z = pk2(p1[12], p1[13]); w.w = pk2(p1[14], p1[15]); pa[3] = __builtin_bit_cast(bf16x8, w); }
;             if (DQK > 96) { AT_PV(vcur); } else {
;                 if (!VPRE) { const LAS unsigned char* vp_ = lds + VBUF + vcur + ((lane >> 4) & 1) * 32 + (lane & 3) * 8 + (4 * hi + ((lane & 15) >> 2)) * 64;
; #pragma unroll
;                     for (int d = 0; d < 2; ++d)
; #pragma unroll
;                         for (int ks = 0; ks < 4; ++ks) { vlo[d * 4 + ks] = vtr(vp_ + d * 4096 + ks * 1024); vhi[d * 4 + ks] = vtr(vp_ + d * 4096 + ks * 1024 + 512); }
;                     __builtin_amdgcn_sched_barrier(0); }
; #pragma unroll
;                 for (int ks = 0; ks < 4; ++ks) {
; #pragma unroll
;                     for (int d = 0; d < 2; ++d) { const s16x4 lo = vlo[d * 4 + ks], hh = vhi[d * 4 + ks];
;                         const bf16x8 vf = (bf16x8){lo[0], lo[1], lo[2], lo[3], hh[0], hh[1], hh[2], hh[3]}; o[d] = MFMA32(pa[ks], vf, o[d]); }
;                     lacc = MFMA32(pa[ks], ones, lacc); }
.LBB0_200:
	v_exp_f32_e32 v64, v64
	v_exp_f32_e32 v65, v65
	v_exp_f32_e32 v66, v66
	v_exp_f32_e32 v67, v67
	v_exp_f32_e32 v68, v68
	v_exp_f32_e32 v69, v69
	v_exp_f32_e32 v70, v70
	v_exp_f32_e32 v71, v71
	v_exp_f32_e32 v80, v80
	v_exp_f32_e32 v81, v81
	v_exp_f32_e32 v82, v82
	v_exp_f32_e32 v83, v83
	v_exp_f32_e32 v194, v72
	v_exp_f32_e32 v201, v73
	v_exp_f32_e32 v203, v74
	v_exp_f32_e32 v204, v75
	v_cvt_pk_bf16_f32 v72, v64, v65
	v_cvt_pk_bf16_f32 v73, v66, v67
	v_cvt_pk_bf16_f32 v74, v68, v69
	v_cvt_pk_bf16_f32 v75, v70, v71
	v_add_f32_e32 v46, v46, v68
	v_add_f32_e32 v47, v47, v69
	v_add_f32_e32 v46, v46, v70
	v_add_f32_e32 v47, v47, v71
	v_cvt_pk_bf16_f32 v68, v80, v81
	v_cvt_pk_bf16_f32 v69, v82, v83
	v_exp_f32_e32 v205, v76
	v_exp_f32_e32 v206, v77
	v_exp_f32_e32 v207, v78
	v_exp_f32_e32 v79, v79
	s_waitcnt lgkmcnt(14)
	v_mfma_f32_32x32x16_bf16 v[0:15], v[72:75], v[148:151], v[0:15]
	v_add_f32_e32 v46, v46, v79
	v_cvt_pk_bf16_f32 v76, v194, v201
	v_cvt_pk_bf16_f32 v77, v203, v204
	v_cvt_pk_bf16_f32 v78, v205, v206
	v_cvt_pk_bf16_f32 v79, v207, v79
	v_add_f32_e32 v47, v47, v64
	v_add_f32_e32 v46, v46, v65
	v_add_f32_e32 v47, v47, v66
	v_add_f32_e32 v46, v46, v67
	v_exp_f32_e32 v84, v84
	v_exp_f32_e32 v85, v85
	v_exp_f32_e32 v86, v86
	s_waitcnt lgkmcnt(6)
	v_mfma_f32_32x32x16_bf16 v[16:31], v[72:75], v[144:147], v[16:31]
	v_exp_f32_e32 v87, v87
	v_cvt_pk_bf16_f32 v70, v84, v85
	v_exp_f32_e32 v88, v88
	v_exp_f32_e32 v89, v89
	v_cvt_pk_bf16_f32 v71, v86, v87
	v_exp_f32_e32 v90, v90
	v_exp_f32_e32 v91, v91
	v_add_f32_e32 v47, v47, v80
	v_add_f32_e32 v46, v46, v81
	v_add_f32_e32 v47, v47, v82
	v_add_f32_e32 v46, v46, v83
	v_exp_f32_e32 v92, v92
	v_exp_f32_e32 v93, v93
	v_exp_f32_e32 v94, v94
	v_exp_f32_e32 v95, v95
	v_cvt_pk_bf16_f32 v64, v88, v89
	v_cvt_pk_bf16_f32 v65, v90, v91
	v_cvt_pk_bf16_f32 v66, v92, v93
	v_mfma_f32_32x32x16_bf16 v[0:15], v[76:79], v[140:143], v[0:15]
	v_cvt_pk_bf16_f32 v67, v94, v95
	s_add_i32 s47, s47, 1
	s_mov_b64 s[40:41], 0x40000
	s_add_i32 s24, s82, s47
	s_add_i32 s46, s46, 1
	v_lshl_add_u64 v[174:175], v[174:175], 0, s[40:41]
	v_lshl_add_u64 v[178:179], v[178:179], 0, s[70:71]
	s_waitcnt lgkmcnt(4)
	v_mfma_f32_32x32x16_bf16 v[16:31], v[76:79], v[136:139], v[16:31]
	v_lshl_add_u64 v[180:181], v[180:181], 0, s[70:71]
	s_cmp_eq_u32 s24, 2
	v_add_f32_e32 v47, v47, v194
	v_add_f32_e32 v46, v46, v201
	v_add_f32_e32 v47, v47, v203
	v_add_f32_e32 v46, v46, v204
	v_mfma_f32_32x32x16_bf16 v[0:15], v[68:71], v[132:135], v[0:15]
	v_add_f32_e32 v47, v47, v205
	v_add_f32_e32 v46, v46, v206
	v_add_f32_e32 v47, v47, v207
	v_add_f32_e32 v46, v46, v84
	s_waitcnt lgkmcnt(2)
	v_mfma_f32_32x32x16_bf16 v[16:31], v[68:71], v[128:131], v[16:31]
	v_add_f32_e32 v47, v47, v85
	v_add_f32_e32 v46, v46, v86
	v_add_f32_e32 v47, v47, v87
	v_add_f32_e32 v46, v46, v88
	v_mfma_f32_32x32x16_bf16 v[0:15], v[64:67], v[120:123], v[0:15]
	v_add_f32_e32 v47, v47, v89
	v_add_f32_e32 v46, v46, v90
	v_add_f32_e32 v47, v47, v91
	v_add_f32_e32 v46, v46, v92
	s_waitcnt lgkmcnt(0)
	v_mfma_f32_32x32x16_bf16 v[16:31], v[64:67], v[124:127], v[16:31]
	v_add_f32_e32 v47, v47, v93
	v_add_f32_e32 v46, v46, v94
	v_add_f32_e32 v47, v47, v95
	s_cbranch_scc1 .LBB0_167
	s_mov_b32 s49, s48
	s_add_i32 s24, s47, -1
	s_cmp_ge_u32 s24, s69
	s_mov_b64 s[40:41], -1
	s_cbranch_scc1 .LBB0_187
	s_branch .LBB0_188

; #define LAS __attribute__((address_space(3)))
; #define GASA __attribute__((address_space(1)))
; DI unsigned pk2(float lo, float hi) { f32x2 v = {lo, hi}; bf16x2_t b = __builtin_convertvector(v, bf16x2_t); return __builtin_bit_cast(unsigned, b); }
; template <int DQK, int DV, bool BAND>
; DI void attn_unit(const AttnArgs& a, LAS unsigned char* lds, int tid) {
;     ...
;     asm volatile("s_waitcnt lgkmcnt(0)\n\ts_barrier" ::: "memory");
;     __builtin_amdgcn_s_setprio(0);
;     { if (a.lse != nullptr) {
;           if (hi == 0) scr[r32] = m_run;
; #pragma unroll
;           for (int g = 0; g < 4; ++g) { const f32x4 mr = *(const LAS f32x4*)(scr + 8 * g + 4 * hi);
; #pragma unroll
;               for (int e = 0; e < 4; ++e) if (r32 == 0) ((GASA float*)a.lse)[(long)(wid * 32 + 8 * g + 4 * hi + e) * a.lses] = mr[e] + __builtin_amdgcn_logf(lacc[4 * g + e]); } }
;       LAS bf16_t* stg = (LAS bf16_t*)(lds + wid * 8192);
; #pragma unroll
;       for (int g = 0; g < 4; ++g) {
; #pragma unroll
;           for (int e = 0; e < 4; ++e) { const int orow = 8 * g + 4 * hi + e; const float rr = __builtin_amdgcn_rcpf(lacc[4 * g + e]);
; #pragma unroll
;               for (int d = 0; d < NDB; ++d) stg[orow * DV + d * 32 + r32] = (bf16_t)(pk2(o[d][4 * g + e] * rr, 0.f) & 0xffffu); } }
;       constexpr int CPR = DV / 8, RPI = 64 / CPR;
; #pragma unroll
;       for (int i = 0; i < 32 / RPI; ++i) { const int row = i * RPI + lane / CPR, ch = lane % CPR;
;           const u32x4 v = *(const LAS u32x4*)(stg + row * DV + ch * 8); *(GASA u32x4*)((GASA bf16_t*)a.o + (long)(wid * 32 + row) * a.os + ch * 8) = v; }
.LBB0_234:
	s_lshl_b64 s[18:19], s[42:43], 11
	s_add_u32 s17, s72, s18
	s_waitcnt lgkmcnt(0)
	s_barrier
	s_addc_u32 s18, s73, s19
	s_add_u32 s40, s17, s46
	s_addc_u32 s41, s18, s47
	s_setprio 0
	s_nop 4
	v_add_f32_e32 v32, v32, v33
	s_nop 0
	v_mov_b32_e32 v33, v32
	s_nop 1
	v_permlane32_swap_b32_e32 v32, v33
	s_nop 1
	v_add_f32_e32 v32, v32, v33
	ds_write_b32 v151, v32
	s_waitcnt lgkmcnt(0)
	ds_read_b128 v[32:35], v153
	ds_read_b128 v[36:39], v153 offset:32
	ds_read_b128 v[40:43], v153 offset:64
	ds_read_b128 v[44:47], v153 offset:96
	s_waitcnt lgkmcnt(0)
	v_rcp_f32_e32 v32, v32
	s_lshl_b32 s16, s16, 13
	s_add_i32 s16, s16, 0
	v_lshlrev_b32_e32 v48, 1, v160
	v_mul_f32_e32 v0, v0, v32
	v_add3_u32 v48, s16, v48, v165
	v_cvt_pk_bf16_f32 v0, v0, s0
	ds_write_b16 v48, v0
	v_rcp_f32_e32 v0, v33
	v_mul_f32_e32 v16, v16, v32
	v_cvt_pk_bf16_f32 v16, v16, s0
	ds_write_b16 v48, v16 offset:64
	v_mul_f32_e32 v1, v1, v0
	v_cvt_pk_bf16_f32 v1, v1, s0
	ds_write_b16 v48, v1 offset:128
	v_rcp_f32_e32 v1, v34
	v_mul_f32_e32 v0, v17, v0
	v_cvt_pk_bf16_f32 v0, v0, s0
	ds_write_b16 v48, v0 offset:192
	v_mul_f32_e32 v0, v2, v1
	v_cvt_pk_bf16_f32 v0, v0, s0
	ds_write_b16 v48, v0 offset:256
	v_rcp_f32_e32 v0, v35
	v_mul_f32_e32 v1, v18, v1
	v_cvt_pk_bf16_f32 v1, v1, s0
	ds_write_b16 v48, v1 offset:320
	v_mul_f32_e32 v1, v3, v0
	v_cvt_pk_bf16_f32 v1, v1, s0
	ds_write_b16 v48, v1 offset:384
	v_rcp_f32_e32 v1, v36
	v_mul_f32_e32 v0, v19, v0
	v_cvt_pk_bf16_f32 v0, v0, s0
	ds_write_b16 v48, v0 offset:448
	v_mul_f32_e32 v0, v4, v1
	v_cvt_pk_bf16_f32 v0, v0, s0
	ds_write_b16 v48, v0 offset:1024
	v_rcp_f32_e32 v0, v37
	v_mul_f32_e32 v1, v20, v1
	v_cvt_pk_bf16_f32 v1, v1, s0
	ds_write_b16 v48, v1 offset:1088
	v_mul_f32_e32 v1, v5, v0
	v_cvt_pk_bf16_f32 v1, v1, s0
	ds_write_b16 v48, v1 offset:1152
	v_rcp_f32_e32 v1, v38
	v_mul_f32_e32 v0, v21, v0
	v_cvt_pk_bf16_f32 v0, v0, s0
	ds_write_b16 v48, v0 offset:1216
	v_mul_f32_e32 v0, v6, v1
	v_cvt_pk_bf16_f32 v0, v0, s0
	ds_write_b16 v48, v0 offset:1280
	v_rcp_f32_e32 v0, v39
	v_mul_f32_e32 v1, v22, v1
	v_cvt_pk_bf16_f32 v1, v1, s0
	ds_write_b16 v48, v1 offset:1344
	v_mul_f32_e32 v1, v7, v0
	v_cvt_pk_bf16_f32 v1, v1, s0
	ds_write_b16 v48, v1 offset:1408
	v_rcp_f32_e32 v1, v40
	v_mul_f32_e32 v0, v23, v0
	v_cvt_pk_bf16_f32 v0, v0, s0
	ds_write_b16 v48, v0 offset:1472
	v_mul_f32_e32 v0, v8, v1
	v_cvt_pk_bf16_f32 v0, v0, s0
	ds_write_b16 v48, v0 offset:2048
	v_rcp_f32_e32 v0, v41
	v_mul_f32_e32 v1, v24, v1
	v_cvt_pk_bf16_f32 v1, v1, s0
	ds_write_b16 v48, v1 offset:2112
	v_mul_f32_e32 v1, v9, v0
	v_cvt_pk_bf16_f32 v1, v1, s0
	ds_write_b16 v48, v1 offset:2176
	v_rcp_f32_e32 v1, v42
	v_mul_f32_e32 v0, v25, v0
	v_cvt_pk_bf16_f32 v0, v0, s0
	ds_write_b16 v48, v0 offset:2240
	v_mul_f32_e32 v0, v10, v1
	v_cvt_pk_bf16_f32 v0, v0, s0
	ds_write_b16 v48, v0 offset:2304
	v_rcp_f32_e32 v0, v43
	v_mul_f32_e32 v1, v26, v1
	v_cvt_pk_bf16_f32 v1, v1, s0
	ds_write_b16 v48, v1 offset:2368
	v_mul_f32_e32 v1, v11, v0
	v_cvt_pk_bf16_f32 v1, v1, s0
	ds_write_b16 v48, v1 offset:2432
	v_rcp_f32_e32 v1, v44
	v_mul_f32_e32 v0, v27, v0
	v_cvt_pk_bf16_f32 v0, v0, s0
	ds_write_b16 v48, v0 offset:2496
	v_mul_f32_e32 v0, v12, v1
	v_cvt_pk_bf16_f32 v0, v0, s0
	ds_write_b16 v48, v0 offset:3072
	v_rcp_f32_e32 v0, v45
	v_mul_f32_e32 v1, v28, v1
	v_cvt_pk_bf16_f32 v1, v1, s0
	ds_write_b16 v48, v1 offset:3136
	v_mul_f32_e32 v1, v13, v0
	v_cvt_pk_bf16_f32 v1, v1, s0
	ds_write_b16 v48, v1 offset:3200
	v_rcp_f32_e32 v1, v46
	v_mul_f32_e32 v0, v29, v0
	v_cvt_pk_bf16_f32 v0, v0, s0
	ds_write_b16 v48, v0 offset:3264
	v_mul_f32_e32 v0, v14, v1
	v_cvt_pk_bf16_f32 v0, v0, s0
	ds_write_b16 v48, v0 offset:3328
	v_rcp_f32_e32 v0, v47
	v_mul_f32_e32 v1, v30, v1
	v_cvt_pk_bf16_f32 v1, v1, s0
	ds_write_b16 v48, v1 offset:3392
	v_mul_f32_e32 v1, v15, v0
	v_mul_f32_e32 v0, v31, v0
	v_cvt_pk_bf16_f32 v0, v0, s0
	v_add_u32_e32 v10, s16, v154
	v_cvt_pk_bf16_f32 v1, v1, s0
	ds_write_b16 v48, v0 offset:3520
	v_add_u32_e32 v0, v10, v167
	ds_write_b16 v48, v1 offset:3456
	ds_read_b128 v[0:3], v0
	v_or_b32_e32 v4, s13, v166
	v_ashrrev_i32_e32 v5, 31, v4
	v_lshlrev_b64 v[4:5], 11, v[4:5]
	v_lshl_add_u64 v[4:5], s[40:41], 0, v[4:5]
	v_mov_b32_e32 v155, v195
	v_lshl_add_u64 v[8:9], v[4:5], 0, v[154:155]
	v_add_u32_e32 v4, v10, v169
	ds_read_b128 v[4:7], v4
	s_waitcnt lgkmcnt(1)
	global_store_dwordx4 v[8:9], v[0:3], off
	s_add_i32 s12, s12, s58
	s_nop 0
	v_or_b32_e32 v0, s13, v168
	v_ashrrev_i32_e32 v1, 31, v0
	v_lshlrev_b64 v[0:1], 11, v[0:1]
	v_lshl_add_u64 v[0:1], s[40:41], 0, v[0:1]
	v_lshl_add_u64 v[0:1], v[0:1], 0, v[154:155]
	s_waitcnt lgkmcnt(0)
	global_store_dwordx4 v[0:1], v[4:7], off
	v_add_u32_e32 v0, v10, v171
	ds_read_b128 v[0:3], v0
	v_or_b32_e32 v4, s13, v170
	v_ashrrev_i32_e32 v5, 31, v4
	v_lshlrev_b64 v[4:5], 11, v[4:5]
	v_lshl_add_u64 v[4:5], s[40:41], 0, v[4:5]
	v_lshl_add_u64 v[8:9], v[4:5], 0, v[154:155]
	v_add_u32_e32 v4, v10, v173
	ds_read_b128 v[4:7], v4
	s_waitcnt lgkmcnt(1)
	global_store_dwordx4 v[8:9], v[0:3], off
	s_nop 1
	v_or_b32_e32 v0, s13, v172
	v_ashrrev_i32_e32 v1, 31, v0
	v_lshlrev_b64 v[0:1], 11, v[0:1]
	v_lshl_add_u64 v[0:1], s[40:41], 0, v[0:1]
	v_readlane_b32 s13, v254, 23
	v_lshl_add_u64 v[0:1], v[0:1], 0, v[154:155]
	s_cmp_ge_i32 s12, s13
	s_waitcnt lgkmcnt(0)
	global_store_dwordx4 v[0:1], v[4:7], off
	s_barrier
	s_cbranch_scc1 .LBB0_259

; #define LAS __attribute__((address_space(3)))
; template <int DQK, int DV, bool BAND>
; DI void attn_unit(const AttnArgs& a, LAS unsigned char* lds, int tid) {
;     ...
;                 if (!first) {
;                     const float alpha = __builtin_amdgcn_exp2f(-delta);
;                     if (hi == 0) scr[r32] = alpha;
; #pragma unroll
;                     for (int g = 0; g < 4; ++g) { const f32x4 al = *(const LAS f32x4*)(scr + 8 * g + 4 * hi);
;                         lacc[4 * g] *= al.x; lacc[4 * g + 1] *= al.y; lacc[4 * g + 2] *= al.z; lacc[4 * g + 3] *= al.w;
; #pragma unroll
;                         for (int d = 0; d < NDB; ++d) { o[d][4 * g] *= al.x; o[d][4 * g + 1] *= al.y; o[d][4 * g + 2] *= al.z; o[d][4 * g + 3] *= al.w; } }
.LBB0_251:
	s_and_saveexec_b64 s[52:53], s[54:55]
	s_cbranch_execz .LBB0_255
	v_exp_f32_e64 v48, -v174
	s_and_saveexec_b64 s[54:55], s[0:1]
	ds_write_b32 v151, v48
	s_or_b64 exec, exec, s[54:55]
	v_mul_f32_e32 v32, v32, v48
	v_mul_f32_e32 v33, v33, v48
	ds_read_b128 v[48:51], v153 offset:96
	ds_read_b128 v[52:55], v153 offset:64
	ds_read_b128 v[56:59], v153 offset:32
	ds_read_b128 v[60:63], v153
	s_waitcnt lgkmcnt(3)
	v_pk_mul_f32 v[30:31], v[30:31], v[50:51]
	s_waitcnt lgkmcnt(2)
	v_pk_mul_f32 v[26:27], v[26:27], v[54:55]
	s_waitcnt lgkmcnt(1)
	v_pk_mul_f32 v[22:23], v[22:23], v[58:59]
	s_waitcnt lgkmcnt(0)
	v_pk_mul_f32 v[18:19], v[18:19], v[62:63]
	v_pk_mul_f32 v[14:15], v[14:15], v[50:51]
	v_pk_mul_f32 v[10:11], v[10:11], v[54:55]
	v_pk_mul_f32 v[6:7], v[6:7], v[58:59]
	v_pk_mul_f32 v[2:3], v[2:3], v[62:63]
	v_pk_mul_f32 v[28:29], v[28:29], v[48:49]
	v_pk_mul_f32 v[24:25], v[24:25], v[52:53]
	v_pk_mul_f32 v[20:21], v[20:21], v[56:57]
	v_pk_mul_f32 v[16:17], v[16:17], v[60:61]
	v_pk_mul_f32 v[12:13], v[12:13], v[48:49]
	v_pk_mul_f32 v[8:9], v[8:9], v[52:53]
	v_pk_mul_f32 v[4:5], v[4:5], v[56:57]
	v_pk_mul_f32 v[0:1], v[0:1], v[60:61]

; #define LAS __attribute__((address_space(3)))
; DI unsigned pk2(float lo, float hi) { f32x2 v = {lo, hi}; bf16x2_t b = __builtin_convertvector(v, bf16x2_t); return __builtin_bit_cast(unsigned, b); }
; #define MFMA32(a, b, c) __builtin_amdgcn_mfma_f32_32x32x16_bf16((a), (b), (c), 0, 0, 0)
; DI s16x4 vtr(const LAS unsigned char* p) { return __builtin_bit_cast(s16x4, __builtin_amdgcn_ds_read_tr16_b64_v4i16((LAS v4i16_t*)p)); }
; template <int DQK, int DV, bool BAND>
; DI void attn_unit(const AttnArgs& a, LAS unsigned char* lds, int tid) {
;     ...
;             for (int r = 0; r < 16; ++r) { p0[r] = __builtin_amdgcn_exp2f(p0[r]); p1[r] = __builtin_amdgcn_exp2f(p1[r]); }
;             { u32x4 w;
;               w.x = pk2(p0[0], p0[1]); w.y = pk2(p0[2], p0[3]); w.z = pk2(p0[4], p0[5]); w.w = pk2(p0[6], p0[7]); pa[0] = __builtin_bit_cast(bf16x8, w);
;               w.x = pk2(p0[8], p0[9]); w.y = pk2(p0[10], p0[11]); w.z = pk2(p0[12], p0[13]); w.w = pk2(p0[14], p0[15]); pa[1] = __builtin_bit_cast(bf16x8, w);
;               w.x = pk2(p1[0], p1[1]); w.y = pk2(p1[2], p1[3]); w.z = pk2(p1[4], p1[5]); w.w = pk2(p1[6], p1[7]); pa[2] = __builtin_bit_cast(bf16x8, w);
;               w.x = pk2(p1[8], p1[9]); w.y = pk2(p1[10], p1[11]); w.z = pk2(p1[12], p1[13]); w.w = pk2(p1[14], p1[15]); pa[3] = __builtin_bit_cast(bf16x8, w); }
;             if (DQK > 96) { AT_PV(vcur); } else {
;                 if (!VPRE) { const LAS unsigned char* vp_ = lds + VBUF + vcur + ((lane >> 4) & 1) * 32 + (lane & 3) * 8 + (4 * hi + ((lane & 15) >> 2)) * 64;
; #pragma unroll
;                     for (int d = 0; d < 2; ++d)
; #pragma unroll
;                         for (int ks = 0; ks < 4; ++ks) { vlo[d * 4 + ks] = vtr(vp_ + d * 4096 + ks * 1024); vhi[d * 4 + ks] = vtr(vp_ + d * 4096 + ks * 1024 + 512); }
;                     __builtin_amdgcn_sched_barrier(0); }
; #pragma unroll
;                 for (int ks = 0; ks < 4; ++ks) {
; #pragma unroll
;                     for (int d = 0; d < 2; ++d) { const s16x4 lo = vlo[d * 4 + ks], hh = vhi[d * 4 + ks];
;                         const bf16x8 vf = (bf16x8){lo[0], lo[1], lo[2], lo[3], hh[0], hh[1], hh[2], hh[3]}; o[d] = MFMA32(pa[ks], vf, o[d]); }
;                     lacc = MFMA32(pa[ks], ones, lacc); }
.LBB0_257:
	s_or_b64 exec, exec, s[50:51]
	v_exp_f32_e32 v64, v64
	v_exp_f32_e32 v65, v65
	v_exp_f32_e32 v66, v66
	v_exp_f32_e32 v67, v67
	v_exp_f32_e32 v68, v68
	v_exp_f32_e32 v69, v69
	v_exp_f32_e32 v70, v70
	v_exp_f32_e32 v71, v71
	v_exp_f32_e32 v80, v80
	v_exp_f32_e32 v81, v81
	v_exp_f32_e32 v82, v82
	v_exp_f32_e32 v83, v83
	v_exp_f32_e32 v174, v72
	v_exp_f32_e32 v175, v73
	v_exp_f32_e32 v178, v74
	v_exp_f32_e32 v179, v75
	v_cvt_pk_bf16_f32 v72, v64, v65
	v_cvt_pk_bf16_f32 v73, v66, v67
	v_cvt_pk_bf16_f32 v74, v68, v69
	v_cvt_pk_bf16_f32 v75, v70, v71
	v_add_f32_e32 v32, v32, v68
	v_add_f32_e32 v33, v33, v69
	v_add_f32_e32 v32, v32, v70
	v_add_f32_e32 v33, v33, v71
	v_cvt_pk_bf16_f32 v68, v80, v81
	v_cvt_pk_bf16_f32 v69, v82, v83
	v_exp_f32_e32 v180, v76
	v_exp_f32_e32 v181, v77
	v_exp_f32_e32 v182, v78
	v_exp_f32_e32 v79, v79
	s_waitcnt lgkmcnt(14)
	v_mfma_f32_32x32x16_bf16 v[0:15], v[72:75], v[140:143], v[0:15]
	v_add_f32_e32 v32, v32, v79
	v_cvt_pk_bf16_f32 v76, v174, v175
	v_cvt_pk_bf16_f32 v77, v178, v179
	v_cvt_pk_bf16_f32 v78, v180, v181
	v_cvt_pk_bf16_f32 v79, v182, v79
	v_add_f32_e32 v33, v33, v64
	v_add_f32_e32 v32, v32, v65
	v_add_f32_e32 v33, v33, v66
	v_add_f32_e32 v32, v32, v67
	v_exp_f32_e32 v84, v84
	v_exp_f32_e32 v85, v85
	v_exp_f32_e32 v86, v86
	s_waitcnt lgkmcnt(6)
	v_mfma_f32_32x32x16_bf16 v[16:31], v[72:75], v[136:139], v[16:31]
	v_exp_f32_e32 v87, v87
	v_cvt_pk_bf16_f32 v70, v84, v85
	v_exp_f32_e32 v88, v88
	v_exp_f32_e32 v89, v89
	v_cvt_pk_bf16_f32 v71, v86, v87
	v_exp_f32_e32 v90, v90
	v_exp_f32_e32 v91, v91
	v_add_f32_e32 v33, v33, v80
	v_add_f32_e32 v32, v32, v81
	v_add_f32_e32 v33, v33, v82
	v_add_f32_e32 v32, v32, v83
	v_exp_f32_e32 v92, v92
	v_exp_f32_e32 v93, v93
	v_exp_f32_e32 v94, v94
	v_exp_f32_e32 v95, v95
	v_cvt_pk_bf16_f32 v64, v88, v89
	v_cvt_pk_bf16_f32 v65, v90, v91
	v_cvt_pk_bf16_f32 v66, v92, v93
	v_mfma_f32_32x32x16_bf16 v[0:15], v[76:79], v[132:135], v[0:15]
	v_cvt_pk_bf16_f32 v67, v94, v95
	v_lshl_add_u64 v[156:157], v[156:157], 0, s[76:77]
	v_lshl_add_u64 v[158:159], v[158:159], 0, s[76:77]
	s_cmp_eq_u32 s69, s19
	v_add_f32_e32 v33, v33, v174
	v_add_f32_e32 v32, v32, v175
	v_add_f32_e32 v33, v33, v178
	v_add_f32_e32 v32, v32, v179
	s_waitcnt lgkmcnt(4)
	v_mfma_f32_32x32x16_bf16 v[16:31], v[76:79], v[128:131], v[16:31]
	v_add_f32_e32 v33, v33, v180
	v_add_f32_e32 v32, v32, v181
	v_add_f32_e32 v33, v33, v182
	v_add_f32_e32 v32, v32, v84
	v_mfma_f32_32x32x16_bf16 v[0:15], v[68:71], v[124:127], v[0:15]
	v_add_f32_e32 v33, v33, v85
	v_add_f32_e32 v32, v32, v86
	v_add_f32_e32 v33, v33, v87
	v_add_f32_e32 v32, v32, v88
	s_waitcnt lgkmcnt(2)
	v_mfma_f32_32x32x16_bf16 v[16:31], v[68:71], v[120:123], v[16:31]
	v_add_f32_e32 v33, v33, v89
	v_add_f32_e32 v32, v32, v90
	v_add_f32_e32 v33, v33, v91
	v_add_f32_e32 v32, v32, v92
	v_mfma_f32_32x32x16_bf16 v[0:15], v[64:67], v[112:115], v[0:15]
	v_add_f32_e32 v33, v33, v93
	v_add_f32_e32 v32, v32, v94
	v_add_f32_e32 v33, v33, v95
	s_waitcnt lgkmcnt(0)
	v_mfma_f32_32x32x16_bf16 v[16:31], v[64:67], v[116:119], v[16:31]
	s_cbranch_scc1 .LBB0_234
	s_mov_b32 s26, s24
	s_mov_b32 s27, s19
	s_add_i32 s19, s27, 1
	s_cmp_ge_u32 s19, s69
	s_mov_b64 s[40:41], -1
	s_cbranch_scc1 .LBB0_238
	s_branch .LBB0_239
